# NA attention: the 16 exec-masked serialised rpb-bias LDS reads per 32-key block become one batch of 16 ds_read_b32 + SALU-combined masks + v_cndmask (no branches, one LDS round trip)
# speedup vs baseline: 1.0408x; 1.0408x over previous
.LBB0_2302:
	s_add_i32 s78, s80, s76
	v_cmp_ge_u32_e32 vcc, s78, v141
	v_cmp_le_u32_e64 s[50:51], s78, v143
	s_and_b64 s[50:51], vcc, s[50:51]
	v_mov_b32_e32 v15, v99
	v_mov_b32_e32 v14, v98
	v_mov_b32_e32 v13, v95
	v_mov_b32_e32 v12, v94
	v_mov_b32_e32 v11, v45
	v_mov_b32_e32 v10, v44
	v_mov_b32_e32 v9, v41
	v_mov_b32_e32 v8, v40
	v_mov_b32_e32 v7, v37
	v_mov_b32_e32 v6, v36
	v_mov_b32_e32 v5, v35
	v_mov_b32_e32 v4, v34
	v_mov_b32_e32 v3, v111
	v_mov_b32_e32 v2, v110
	v_mov_b32_e32 v1, v109
	v_mov_b32_e32 v0, v108
	v_mov_b32_e32 v31, v107
	v_mov_b32_e32 v30, v106
	v_mov_b32_e32 v29, v105
	v_mov_b32_e32 v28, v104
	v_mov_b32_e32 v27, v103
	v_mov_b32_e32 v26, v102
	v_mov_b32_e32 v25, v101
	v_mov_b32_e32 v24, v100
	v_mov_b32_e32 v23, v97
	v_mov_b32_e32 v22, v96
	v_mov_b32_e32 v21, v47
	v_mov_b32_e32 v20, v46
	v_mov_b32_e32 v19, v43
	v_mov_b32_e32 v18, v42
	v_mov_b32_e32 v17, v39
	v_mov_b32_e32 v16, v38
	v_mov_b32_e32 v145, v112
	v_mov_b32_e32 v113, v76
	s_and_saveexec_b64 s[76:77], s[50:51]
	s_cbranch_execz .LBB0_2336
	v_add3_u32 v20, s90, v128, v74
	ds_read_b128 v[0:3], v20
	ds_read_b128 v[16:19], v20 offset:32
	v_cmp_ge_u32_e32 vcc, s78, v142
	v_cmp_lt_u32_e64 s[50:51], s78, v144
	s_and_b64 s[50:51], vcc, s[50:51]
	s_waitcnt lgkmcnt(1)
	v_mfma_f32_32x32x16_bf16 v[0:15], v[0:3], v[48:51], 0
	s_waitcnt lgkmcnt(0)
	v_mfma_f32_32x32x16_bf16 v[0:15], v[16:19], v[52:55], v[0:15]
	ds_read_b128 v[16:19], v20 offset:64
	ds_read_b128 v[20:23], v20 offset:96
	s_waitcnt lgkmcnt(1)
	v_mfma_f32_32x32x16_bf16 v[0:15], v[16:19], v[56:59], v[0:15]
	v_mov_b32_e32 v16, 0xff800000
	v_mov_b32_e32 v17, 0xff800000
	s_waitcnt lgkmcnt(0)
	v_mfma_f32_32x32x16_bf16 v[0:15], v[20:23], v[60:63], v[0:15]
	ds_read_b32 v236, v85
	ds_read_b32 v237, v85 offset:4
	ds_read_b32 v238, v85 offset:8
	ds_read_b32 v239, v85 offset:12
	ds_read_b32 v240, v85 offset:32
	ds_read_b32 v241, v85 offset:36
	ds_read_b32 v242, v85 offset:40
	ds_read_b32 v243, v85 offset:44
	ds_read_b32 v244, v85 offset:64
	ds_read_b32 v245, v85 offset:68
	ds_read_b32 v246, v85 offset:72
	ds_read_b32 v247, v85 offset:76
	ds_read_b32 v248, v85 offset:96
	ds_read_b32 v249, v85 offset:100
	ds_read_b32 v250, v85 offset:104
	s_waitcnt lgkmcnt(8)
	ds_read_b32 v251, v85 offset:108
	s_and_b64 s[78:79], s[50:51], s[8:9]
	v_add_f32_e32 v236, v0, v236
	v_cndmask_b32_e64 v17, v140, v236, s[78:79]
	s_andn2_b64 s[78:79], s[50:51], s[10:11]
	v_add_f32_e32 v237, v1, v237
	v_cndmask_b32_e64 v16, v140, v237, s[78:79]
	s_andn2_b64 s[78:79], s[50:51], s[12:13]
	v_add_f32_e32 v238, v2, v238
	v_cndmask_b32_e64 v1, v140, v238, s[78:79]
	s_andn2_b64 s[78:79], s[50:51], s[14:15]
	v_add_f32_e32 v239, v3, v239
	v_cndmask_b32_e64 v0, v140, v239, s[78:79]
	s_andn2_b64 s[78:79], s[50:51], s[16:17]
	v_add_f32_e32 v240, v4, v240
	v_cndmask_b32_e64 v3, v140, v240, s[78:79]
	s_andn2_b64 s[78:79], s[50:51], s[18:19]
	v_add_f32_e32 v241, v5, v241
	v_cndmask_b32_e64 v2, v140, v241, s[78:79]
	s_andn2_b64 s[78:79], s[50:51], s[20:21]
	v_add_f32_e32 v242, v6, v242
	v_cndmask_b32_e64 v5, v140, v242, s[78:79]
	s_waitcnt lgkmcnt(0)
	s_andn2_b64 s[78:79], s[50:51], s[22:23]
	v_add_f32_e32 v243, v7, v243
	v_cndmask_b32_e64 v4, v140, v243, s[78:79]
	s_and_b64 s[78:79], s[50:51], s[24:25]
	v_add_f32_e32 v244, v8, v244
	v_cndmask_b32_e64 v7, v140, v244, s[78:79]
	s_and_b64 s[78:79], s[50:51], s[26:27]
	v_add_f32_e32 v245, v9, v245
	v_cndmask_b32_e64 v6, v140, v245, s[78:79]
	s_andn2_b64 s[78:79], s[50:51], s[28:29]
	v_add_f32_e32 v246, v10, v246
	v_cndmask_b32_e64 v9, v140, v246, s[78:79]
	s_andn2_b64 s[78:79], s[50:51], s[30:31]
	v_add_f32_e32 v247, v11, v247
	v_cndmask_b32_e64 v8, v140, v247, s[78:79]
	s_andn2_b64 s[78:79], s[50:51], s[34:35]
	v_add_f32_e32 v248, v12, v248
	v_cndmask_b32_e64 v11, v140, v248, s[78:79]
	s_andn2_b64 s[78:79], s[50:51], s[36:37]
	v_add_f32_e32 v249, v13, v249
	v_cndmask_b32_e64 v10, v140, v249, s[78:79]
	s_andn2_b64 s[78:79], s[50:51], s[38:39]
	v_add_f32_e32 v250, v14, v250
	v_cndmask_b32_e64 v13, v140, v250, s[78:79]
	s_andn2_b64 s[78:79], s[50:51], s[40:41]
	v_add_f32_e32 v251, v15, v251
	v_cndmask_b32_e64 v12, v140, v251, s[78:79]
	v_max_f32_e32 v14, v16, v16
	v_max_f32_e32 v15, v17, v17
	v_max_f32_e32 v14, v15, v14
	v_max3_f32 v14, v14, v1, v0
	v_max3_f32 v14, v14, v3, v2
	v_max3_f32 v14, v14, v5, v4
	v_max3_f32 v14, v14, v7, v6
	v_max3_f32 v14, v14, v9, v8
	v_max3_f32 v14, v14, v11, v10
	v_max3_f32 v14, v14, v13, v12
	ds_bpermute_b32 v15, v130, v14
	v_add3_u32 v146, s90, v131, v129
	v_add_u32_e32 v162, 0x4800, v146
	ds_read2_b64 v[114:117], v162 offset1:2
	s_waitcnt lgkmcnt(1)
	v_max3_f32 v145, v112, v14, v15
	v_cmp_neq_f32_e32 vcc, s82, v145
	s_nop 1
	v_cndmask_b32_e32 v14, 0, v145, vcc
	v_sub_f32_e32 v0, v0, v14
	v_exp_f32_e32 v123, v0
	v_sub_f32_e32 v0, v3, v14
	v_exp_f32_e32 v150, v0
	v_sub_f32_e32 v0, v2, v14
	v_exp_f32_e32 v151, v0
	v_sub_f32_e32 v0, v5, v14
	v_exp_f32_e32 v152, v0
	v_sub_f32_e32 v0, v4, v14
	v_exp_f32_e32 v153, v0
	v_sub_f32_e32 v0, v7, v14
	v_exp_f32_e32 v154, v0
	v_sub_f32_e32 v0, v6, v14
	v_exp_f32_e32 v155, v0
	v_sub_f32_e32 v0, v9, v14
	v_sub_f32_e32 v15, v112, v14
	v_sub_f32_e32 v17, v17, v14
	v_sub_f32_e32 v16, v16, v14
	v_exp_f32_e32 v156, v0
	v_sub_f32_e32 v0, v8, v14
	v_exp_f32_e32 v33, v17
	v_exp_f32_e32 v113, v16
	v_exp_f32_e32 v157, v0
	v_sub_f32_e32 v0, v11, v14
	v_exp_f32_e32 v32, v15
	v_exp_f32_e32 v158, v0
	v_sub_f32_e32 v0, v10, v14
	v_exp_f32_e32 v159, v0
	v_sub_f32_e32 v0, v13, v14
	v_sub_f32_e32 v1, v1, v14
	v_exp_f32_e32 v160, v0
	v_sub_f32_e32 v0, v12, v14
	v_exp_f32_e32 v122, v1
	v_exp_f32_e32 v161, v0
	v_pk_mul_f32 v[16:17], v[38:39], v[32:33] op_sel_hi:[1,0]
	v_pk_mul_f32 v[18:19], v[42:43], v[32:33] op_sel_hi:[1,0]
	v_pk_mul_f32 v[20:21], v[46:47], v[32:33] op_sel_hi:[1,0]
	v_pk_mul_f32 v[22:23], v[96:97], v[32:33] op_sel_hi:[1,0]
	v_pk_mul_f32 v[24:25], v[100:101], v[32:33] op_sel_hi:[1,0]
	v_pk_mul_f32 v[26:27], v[102:103], v[32:33] op_sel_hi:[1,0]
	v_pk_mul_f32 v[28:29], v[104:105], v[32:33] op_sel_hi:[1,0]
	v_pk_mul_f32 v[30:31], v[106:107], v[32:33] op_sel_hi:[1,0]
	v_pk_mul_f32 v[0:1], v[108:109], v[32:33] op_sel_hi:[1,0]
	v_pk_mul_f32 v[2:3], v[110:111], v[32:33] op_sel_hi:[1,0]
	v_pk_mul_f32 v[4:5], v[34:35], v[32:33] op_sel_hi:[1,0]
	v_pk_mul_f32 v[6:7], v[36:37], v[32:33] op_sel_hi:[1,0]
	v_pk_mul_f32 v[8:9], v[40:41], v[32:33] op_sel_hi:[1,0]
	v_pk_mul_f32 v[10:11], v[44:45], v[32:33] op_sel_hi:[1,0]
	v_pk_mul_f32 v[12:13], v[94:95], v[32:33] op_sel_hi:[1,0]
	v_pk_mul_f32 v[14:15], v[98:99], v[32:33] op_sel_hi:[1,0]
	v_add_f32_e32 v163, 0, v33
	v_cvt_pk_bf16_f32 v118, v33, v113
	v_add_u32_e32 v33, 0x5800, v146
	ds_read2_b64 v[146:149], v33 offset0:64 offset1:66
	v_cvt_pk_bf16_f32 v119, v122, v123
	v_cvt_pk_bf16_f32 v120, v150, v151
	v_cvt_pk_bf16_f32 v121, v152, v153
	v_add_f32_e32 v113, v113, v163
	v_add_f32_e32 v113, v122, v113
	s_waitcnt lgkmcnt(1)
	v_mfma_f32_32x32x16_bf16 v[16:31], v[114:117], v[118:121], v[16:31]
	ds_read2_b64 v[114:117], v162 offset0:4 offset1:6
	v_add_f32_e32 v113, v123, v113
	v_add_f32_e32 v113, v150, v113
	v_add_f32_e32 v113, v151, v113
	v_add_f32_e32 v113, v152, v113
	v_add_f32_e32 v113, v153, v113
	v_add_f32_e32 v113, v154, v113
	s_waitcnt lgkmcnt(1)
	v_mfma_f32_32x32x16_bf16 v[0:15], v[146:149], v[118:121], v[0:15]
	ds_read2_b64 v[146:149], v33 offset0:68 offset1:70
	v_cvt_pk_bf16_f32 v118, v154, v155
	v_cvt_pk_bf16_f32 v119, v156, v157
	v_cvt_pk_bf16_f32 v120, v158, v159
	v_cvt_pk_bf16_f32 v121, v160, v161
	v_add_f32_e32 v33, v155, v113
	v_add_f32_e32 v33, v156, v33
	s_waitcnt lgkmcnt(1)
	v_mfma_f32_32x32x16_bf16 v[16:31], v[114:117], v[118:121], v[16:31]
	v_add_f32_e32 v33, v157, v33
	v_add_f32_e32 v33, v158, v33
	v_add_f32_e32 v33, v159, v33
	v_add_f32_e32 v33, v160, v33
	v_add_f32_e32 v113, v161, v33
	v_fmac_f32_e32 v113, v76, v32
	s_waitcnt lgkmcnt(0)
	v_mfma_f32_32x32x16_bf16 v[0:15], v[146:149], v[118:121], v[0:15]
